# LN2 copy: two specialised row loops (stats+H / plain row store) with hoisted gamma/beta, early mod loads, L2 touch, counted vmcnt
# speedup vs baseline: 1.0321x; 1.0065x over previous
.LBB0_15:
	v_readlane_b32 s14, v255, 3
	v_readlane_b32 s15, v255, 4
	v_mov_b32_e32 v0, v254
	s_andn2_b64 vcc, exec, s[14:15]
	s_cbranch_vccnz .LBB0_49
	s_load_dwordx2 s[20:21], s[10:11], 0x118
	v_and_b32_e32 v3, 63, v0
	v_ashrrev_i32_e32 v0, 6, v0
	v_readlane_b32 s2, v255, 23
	v_mov_b32_e32 v33, v149
	v_lshlrev_b32_e32 v148, 4, v3
	v_add_u32_e32 v32, s2, v0
	v_lshlrev_b64 v[0:1], 12, v[32:33]
	s_waitcnt lgkmcnt(0)
	v_lshl_add_u64 v[0:1], s[20:21], 0, v[0:1]
	v_lshl_add_u64 v[0:1], v[0:1], 0, v[148:149]
	global_load_dwordx4 v[16:19], v[0:1], off offset:3072
	global_load_dwordx4 v[20:23], v[0:1], off offset:2048
	global_load_dwordx4 v[24:27], v[0:1], off offset:1024
	global_load_dwordx4 v[28:31], v[0:1], off
	s_lshl_b32 s26, s82, 10
	s_lshl_b64 s[14:15], s[26:27], 2
	s_add_u32 s8, s8, s14
	s_addc_u32 s9, s9, s15
	s_add_u32 s14, s22, s14
	s_addc_u32 s15, s23, s15
	s_cmp_eq_u64 s[12:13], 0
	s_cselect_b64 s[22:23], -1, 0
	s_cmp_lg_u64 s[12:13], 0
	s_cselect_b64 s[16:17], -1, 0
	v_cmp_eq_u32_e32 vcc, 0, v3
	s_and_b64 s[28:29], s[16:17], vcc
	v_lshlrev_b32_e32 v0, 2, v3
	s_cmp_lg_u64 s[6:7], 0
	v_or_b32_e32 v2, 0x100, v0
	v_or_b32_e32 v4, 0x200, v0
	v_or_b32_e32 v6, 0x300, v0
	s_cselect_b64 s[30:31], -1, 0
	v_xor_b32_e32 v62, 64, v0
	v_xor_b32_e32 v63, 0x80, v0
	v_lshl_add_u64 v[34:35], s[8:9], 0, v[148:149]
	v_lshl_add_u64 v[36:37], s[14:15], 0, v[148:149]
	v_cndmask_b32_e64 v64, 0, 1, s[22:23]
	v_mov_b64_e32 v[38:39], s[6:7]
	v_cndmask_b32_e64 v65, 0, 1, s[30:31]
	global_load_dwordx4 v[80:83], v[34:35], off
	global_load_dwordx4 v[84:87], v[34:35], off offset:1024
	global_load_dwordx4 v[88:91], v[34:35], off offset:2048
	global_load_dwordx4 v[92:95], v[34:35], off offset:3072
	global_load_dwordx4 v[96:99], v[36:37], off
	global_load_dwordx4 v[100:103], v[36:37], off offset:1024
	global_load_dwordx4 v[104:107], v[36:37], off offset:2048
	global_load_dwordx4 v[108:111], v[36:37], off offset:3072
	v_and_b32_e32 v74, 31, v3
	v_lshlrev_b32_e32 v74, 7, v74
	v_sub_u32_e32 v74, v74, v148
	v_ashrrev_i32_e32 v75, 31, v74
	s_waitcnt vmcnt(0)
	v_lshlrev_b32_e32 v40, 2, v2
	v_lshlrev_b32_e32 v42, 2, v4
	v_lshlrev_b32_e32 v44, 2, v6
	v_lshlrev_b32_e32 v148, 2, v0
	v_lshlrev_b32_e32 v46, 1, v0
	v_readlane_b32 s2, v255, 0
	s_and_b64 s[14:15], s[30:31], s[16:17]
	s_cbranch_scc1 .Lln2A_top
	s_or_b64 s[14:15], s[30:31], s[16:17]
	s_cbranch_scc0 .Lln2B_top
	s_branch .LBB0_24
.Lln2A_top:
	s_add_i32 s2, s2, s18
	v_ashrrev_i32_e32 v33, 31, v32
	s_cmpk_gt_i32 s2, 0x17ff
	v_lshlrev_b64 v[0:1], 12, v[32:33]
	s_cselect_b64 s[36:37], -1, 0
	v_lshl_add_u64 v[48:49], s[20:21], 0, v[0:1]
	v_add_u32_e32 v64, 0xffffe000, v32
	v_lshrrev_b32_e32 v64, 11, v64
	v_add_u32_e32 v64, 1, v64
	v_cmp_lt_i32_e32 vcc, s34, v32
	s_nop 1
	v_cndmask_b32_e32 v66, 0, v64, vcc
	v_mad_u64_u32 v[64:65], s[14:15], v66, s35, v[38:39]
	s_mov_b64 s[14:15], 0x1000
	s_nop 0
	v_lshl_add_u64 v[68:69], v[64:65], 0, s[14:15]
	v_mov_b32_e32 v41, v149
	v_mov_b32_e32 v43, v149
	v_mov_b32_e32 v45, v149
	v_lshl_add_u64 v[64:65], v[64:65], 0, v[148:149]
	v_lshl_add_u64 v[70:71], v[68:69], 0, v[148:149]
	global_load_dwordx4 v[112:115], v[70:71], off
	v_lshl_add_u64 v[70:71], v[68:69], 0, v[40:41]
	global_load_dwordx4 v[116:119], v[70:71], off
	v_lshl_add_u64 v[70:71], v[68:69], 0, v[42:43]
	global_load_dwordx4 v[120:123], v[70:71], off
	v_lshl_add_u64 v[70:71], v[68:69], 0, v[44:45]
	global_load_dwordx4 v[124:127], v[70:71], off
	global_load_dwordx4 v[128:131], v[64:65], off
	global_load_dwordx4 v[132:135], v[64:65], off offset:1024
	global_load_dwordx4 v[136:139], v[64:65], off offset:2048
	global_load_dwordx4 v[140:143], v[64:65], off offset:3072
	s_and_b64 vcc, exec, s[36:37]
	s_cbranch_vccnz .Lln2A_nopf
	v_readlane_b32 s6, v255, 5
	v_readlane_b32 s7, v255, 6
	s_nop 1
	v_lshl_add_u64 v[0:1], v[48:49], 0, s[6:7]
	v_lshl_add_u64 v[12:13], v[0:1], 0, v[148:149]
	v_lshl_add_u64 v[70:71], v[12:13], 0, v[74:75]
	global_load_dwordx4 v[0:3], v[12:13], off
	global_load_dwordx4 v[4:7], v[12:13], off offset:1024
	global_load_dwordx4 v[8:11], v[12:13], off offset:2048
	s_nop 0
	global_load_dwordx4 v[12:15], v[12:13], off offset:3072
	s_add_i32 s14, s2, s18
	s_cmpk_gt_i32 s14, 0x17ff
	s_cselect_b32 s14, 0, s6
	s_cselect_b32 s15, 0, s7
	v_lshl_add_u64 v[70:71], v[70:71], 0, s[14:15]
	global_load_dword v150, v[70:71], off

.Lln2A_28:
	s_or_b64 exec, exec, s[6:7]
	s_load_dwordx2 s[14:15], s[10:11], 0x120
	s_and_b64 vcc, exec, s[36:37]
	s_cbranch_vccnz .Lln2A_wl
	s_waitcnt vmcnt(6)
	s_branch .Lln2A_wd

.Lln2A_wd:
	v_mov_b32_e32 v27, v26
	v_lshlrev_b64 v[76:77], 10, v[32:33]
	v_mov_b32_e32 v47, v149
	s_waitcnt lgkmcnt(0)
	v_lshl_add_u64 v[76:77], v[76:77], 1, s[14:15]
	s_mov_b64 s[14:15], 0xe0c1000
	v_lshl_add_u64 v[76:77], v[76:77], 0, v[46:47]
	v_lshl_add_u64 v[76:77], v[76:77], 0, s[14:15]
	v_pk_mul_f32 v[64:65], v[58:59], v[26:27]
	v_pk_mul_f32 v[66:67], v[28:29], v[26:27]
	v_pk_add_f32 v[68:69], v[112:113], 1.0 op_sel_hi:[1,0]
	v_pk_add_f32 v[70:71], v[114:115], 1.0 op_sel_hi:[1,0]
	v_pk_fma_f32 v[64:65], v[64:65], v[80:81], v[96:97]
	v_pk_fma_f32 v[66:67], v[66:67], v[82:83], v[98:99]
	v_pk_fma_f32 v[64:65], v[64:65], v[68:69], v[128:129]
	v_pk_fma_f32 v[66:67], v[66:67], v[70:71], v[130:131]
	v_cvt_pk_bf16_f32 v72, v64, v65
	v_cvt_pk_bf16_f32 v73, v66, v67
	global_store_dwordx2 v[76:77], v[72:73], off
	v_pk_mul_f32 v[64:65], v[54:55], v[26:27]
	v_pk_mul_f32 v[66:67], v[56:57], v[26:27]
	v_pk_add_f32 v[68:69], v[116:117], 1.0 op_sel_hi:[1,0]
	v_pk_add_f32 v[70:71], v[118:119], 1.0 op_sel_hi:[1,0]
	v_pk_fma_f32 v[64:65], v[64:65], v[84:85], v[100:101]
	v_pk_fma_f32 v[66:67], v[66:67], v[86:87], v[102:103]
	v_pk_fma_f32 v[64:65], v[64:65], v[68:69], v[132:133]
	v_pk_fma_f32 v[66:67], v[66:67], v[70:71], v[134:135]
	v_cvt_pk_bf16_f32 v72, v64, v65
	v_cvt_pk_bf16_f32 v73, v66, v67
	global_store_dwordx2 v[76:77], v[72:73], off offset:512
	v_pk_mul_f32 v[64:65], v[52:53], v[26:27]
	v_pk_mul_f32 v[66:67], v[50:51], v[26:27]
	v_pk_add_f32 v[68:69], v[120:121], 1.0 op_sel_hi:[1,0]
	v_pk_add_f32 v[70:71], v[122:123], 1.0 op_sel_hi:[1,0]
	v_pk_fma_f32 v[64:65], v[64:65], v[88:89], v[104:105]
	v_pk_fma_f32 v[66:67], v[66:67], v[90:91], v[106:107]
	v_pk_fma_f32 v[64:65], v[64:65], v[68:69], v[136:137]
	v_pk_fma_f32 v[66:67], v[66:67], v[70:71], v[138:139]
	v_cvt_pk_bf16_f32 v72, v64, v65
	v_cvt_pk_bf16_f32 v73, v66, v67
	global_store_dwordx2 v[76:77], v[72:73], off offset:1024
	v_pk_mul_f32 v[64:65], v[22:23], v[26:27]
	v_pk_mul_f32 v[66:67], v[20:21], v[26:27]
	v_pk_add_f32 v[68:69], v[124:125], 1.0 op_sel_hi:[1,0]
	v_pk_add_f32 v[70:71], v[126:127], 1.0 op_sel_hi:[1,0]
	v_pk_fma_f32 v[64:65], v[64:65], v[92:93], v[108:109]
	v_pk_fma_f32 v[66:67], v[66:67], v[94:95], v[110:111]
	v_pk_fma_f32 v[64:65], v[64:65], v[68:69], v[140:141]
	v_pk_fma_f32 v[66:67], v[66:67], v[70:71], v[142:143]
	v_cvt_pk_bf16_f32 v72, v64, v65
	v_cvt_pk_bf16_f32 v73, v66, v67
	global_store_dwordx2 v[76:77], v[72:73], off offset:1536
	v_add_u32_e32 v32, s90, v32
	s_and_b64 vcc, exec, s[36:37]
	s_cbranch_vccnz .LBB0_49
	s_waitcnt vmcnt(6)
	v_mov_b64_e32 v[18:19], v[14:15]
	v_mov_b64_e32 v[16:17], v[12:13]
	v_mov_b64_e32 v[22:23], v[10:11]
	v_mov_b64_e32 v[20:21], v[8:9]
	v_mov_b64_e32 v[26:27], v[6:7]
	v_mov_b64_e32 v[24:25], v[4:5]
	v_mov_b64_e32 v[30:31], v[2:3]
	v_mov_b64_e32 v[28:29], v[0:1]
	s_branch .Lln2A_top
.Lln2B_top:
	s_add_i32 s2, s2, s18
	v_ashrrev_i32_e32 v33, 31, v32
	s_cmpk_gt_i32 s2, 0x17ff
	v_lshlrev_b64 v[0:1], 12, v[32:33]
	s_cselect_b64 s[36:37], -1, 0
	v_lshl_add_u64 v[48:49], s[20:21], 0, v[0:1]
	s_and_b64 vcc, exec, s[36:37]
	s_cbranch_vccnz .Lln2B_nopf
	v_readlane_b32 s6, v255, 5
	v_readlane_b32 s7, v255, 6
	s_nop 1
	v_lshl_add_u64 v[0:1], v[48:49], 0, s[6:7]
	v_lshl_add_u64 v[12:13], v[0:1], 0, v[148:149]
	v_lshl_add_u64 v[70:71], v[12:13], 0, v[74:75]
	global_load_dwordx4 v[0:3], v[12:13], off
	global_load_dwordx4 v[4:7], v[12:13], off offset:1024
	global_load_dwordx4 v[8:11], v[12:13], off offset:2048
	s_nop 0
	global_load_dwordx4 v[12:15], v[12:13], off offset:3072
	s_add_i32 s14, s2, s18
	s_cmpk_gt_i32 s14, 0x17ff
	s_cselect_b32 s14, 0, s6
	s_cselect_b32 s15, 0, s7
	v_lshl_add_u64 v[70:71], v[70:71], 0, s[14:15]
	global_load_dword v150, v[70:71], off

.Lln2B_28:
	s_or_b64 exec, exec, s[6:7]
	v_mov_b32_e32 v27, v26
	v_lshl_add_u64 v[68:69], v[48:49], 0, v[148:149]
	v_pk_mul_f32 v[64:65], v[58:59], v[26:27]
	v_pk_mul_f32 v[66:67], v[28:29], v[26:27]
	v_pk_fma_f32 v[64:65], v[64:65], v[80:81], v[96:97]
	v_pk_fma_f32 v[66:67], v[66:67], v[82:83], v[98:99]
	global_store_dwordx4 v[68:69], v[64:67], off
	v_pk_mul_f32 v[112:113], v[54:55], v[26:27]
	v_pk_mul_f32 v[114:115], v[56:57], v[26:27]
	v_pk_fma_f32 v[112:113], v[112:113], v[84:85], v[100:101]
	v_pk_fma_f32 v[114:115], v[114:115], v[86:87], v[102:103]
	global_store_dwordx4 v[68:69], v[112:115], off offset:1024
	v_pk_mul_f32 v[116:117], v[52:53], v[26:27]
	v_pk_mul_f32 v[118:119], v[50:51], v[26:27]
	v_pk_fma_f32 v[116:117], v[116:117], v[88:89], v[104:105]
	v_pk_fma_f32 v[118:119], v[118:119], v[90:91], v[106:107]
	global_store_dwordx4 v[68:69], v[116:119], off offset:2048
	v_pk_mul_f32 v[120:121], v[22:23], v[26:27]
	v_pk_mul_f32 v[122:123], v[20:21], v[26:27]
	v_pk_fma_f32 v[120:121], v[120:121], v[92:93], v[108:109]
	v_pk_fma_f32 v[122:123], v[122:123], v[94:95], v[110:111]
	global_store_dwordx4 v[68:69], v[120:123], off offset:3072
	v_add_u32_e32 v32, s90, v32
	s_and_b64 vcc, exec, s[36:37]
	s_cbranch_vccnz .LBB0_49
	s_waitcnt vmcnt(5)
	v_mov_b64_e32 v[18:19], v[14:15]
	v_mov_b64_e32 v[16:17], v[12:13]
	v_mov_b64_e32 v[22:23], v[10:11]
	v_mov_b64_e32 v[20:21], v[8:9]
	v_mov_b64_e32 v[26:27], v[6:7]
	v_mov_b64_e32 v[24:25], v[4:5]
	v_mov_b64_e32 v[30:31], v[2:3]
	v_mov_b64_e32 v[28:29], v[0:1]
	s_branch .Lln2B_top
